# poll back-off (s_sleep 6) on the cross-XCD release word at the split seams
# baseline (speedup 1.0000x reference)
.Lg4_poll:
	global_load_dword v1, v0, s[30:31] sc1
	s_waitcnt vmcnt(0)
	v_cmp_le_u32_e32 vcc, s101, v1
	s_cbranch_vccnz .Lg4_got
	s_sleep 6
	s_sub_u32 s100, s100, 1
	s_cmp_lg_u32 s100, 0
	s_cbranch_scc1 .Lg4_poll

.Lwb_poll:
	global_load_dword v177, v176, s[30:31] sc1
	s_waitcnt vmcnt(0)
	v_cmp_lt_u32_e32 vcc, s99, v177
	s_cbranch_vccnz .Lwb_got
	s_sleep 6
	s_sub_u32 s100, s100, 1
	s_cmp_lg_u32 s100, 0
	s_cbranch_scc1 .Lwb_poll
